# removed per-K-step s_setprio flips in the four GEMM loops
# speedup vs baseline: 1.1041x; 1.0006x over previous
.LBB0_713:
	s_and_b32 s16, s7, 1
	s_xor_b32 s17, s16, 1
	s_lshl_b32 s33, s17, 14
	v_lshl_add_u64 v[150:151], v[146:147], 0, s[14:15]
	s_add_i32 s33, s1, s33
	v_lshl_add_u64 v[178:179], v[150:151], 0, 64
	s_mov_b32 m0, s33
	v_lshl_add_u64 v[180:181], v[150:151], 0, s[38:39]
	global_load_lds_dwordx4 v[178:179], off
	s_add_i32 m0, s33, 0x400
	v_lshl_add_u64 v[182:183], v[150:151], 0, s[40:41]
	s_lshl_b32 s17, s17, 13
	global_load_lds_dwordx4 v[180:181], off
	s_add_i32 m0, s33, 0x800
	v_lshl_add_u64 v[172:173], v[148:149], 0, s[14:15]
	v_lshl_add_u64 v[150:151], v[150:151], 0, s[42:43]
	s_add_i32 s17, s6, s17
	global_load_lds_dwordx4 v[182:183], off
	s_add_i32 m0, s33, 0xc00
	v_lshl_add_u64 v[184:185], v[172:173], 0, 64
	global_load_lds_dwordx4 v[150:151], off
	s_add_i32 m0, s17, 0x8000
	v_lshl_add_u64 v[172:173], v[172:173], 0, s[38:39]
	global_load_lds_dwordx4 v[184:185], off
	s_add_i32 m0, s17, 0x8400
	v_lshl_or_b32 v145, s16, 13, v136
	global_load_lds_dwordx4 v[172:173], off
	v_lshl_add_u32 v150, s16, 14, v143
	ds_read_b128 v[178:181], v145 offset:32768
	ds_read_b128 v[182:185], v145 offset:33792
	ds_read_b128 v[186:189], v145 offset:34816
	ds_read_b128 v[190:193], v145 offset:35840
	ds_read_b128 v[194:197], v150
	ds_read_b128 v[198:201], v150 offset:1024
	ds_read_b128 v[202:205], v150 offset:2048
	ds_read_b128 v[206:209], v150 offset:3072
	ds_read_b128 v[210:213], v150 offset:4096
	ds_read_b128 v[214:217], v150 offset:5120
	ds_read_b128 v[218:221], v150 offset:6144
	ds_read_b128 v[222:225], v150 offset:7168
	s_add_i32 s7, s7, 1
	s_waitcnt lgkmcnt(0)
	v_mfma_f32_16x16x32_bf16 v[28:31], v[178:181], v[194:197], v[28:31]
	v_mfma_f32_16x16x32_bf16 v[24:27], v[178:181], v[198:201], v[24:27]
	v_mfma_f32_16x16x32_bf16 v[20:23], v[178:181], v[202:205], v[20:23]
	v_mfma_f32_16x16x32_bf16 v[16:19], v[178:181], v[206:209], v[16:19]
	v_mfma_f32_16x16x32_bf16 v[12:15], v[178:181], v[210:213], v[12:15]
	v_mfma_f32_16x16x32_bf16 v[8:11], v[178:181], v[214:217], v[8:11]
	v_mfma_f32_16x16x32_bf16 v[4:7], v[178:181], v[218:221], v[4:7]
	v_mfma_f32_16x16x32_bf16 v[0:3], v[178:181], v[222:225], v[0:3]
	v_mfma_f32_16x16x32_bf16 v[124:127], v[182:185], v[194:197], v[124:127]
	v_mfma_f32_16x16x32_bf16 v[120:123], v[182:185], v[198:201], v[120:123]
	v_mfma_f32_16x16x32_bf16 v[116:119], v[182:185], v[202:205], v[116:119]
	v_mfma_f32_16x16x32_bf16 v[80:83], v[182:185], v[206:209], v[80:83]
	v_mfma_f32_16x16x32_bf16 v[68:71], v[182:185], v[210:213], v[68:71]
	v_mfma_f32_16x16x32_bf16 v[56:59], v[182:185], v[214:217], v[56:59]
	v_mfma_f32_16x16x32_bf16 v[44:47], v[182:185], v[218:221], v[44:47]
	v_mfma_f32_16x16x32_bf16 v[32:35], v[182:185], v[222:225], v[32:35]
	v_mfma_f32_16x16x32_bf16 v[112:115], v[186:189], v[194:197], v[112:115]
	v_mfma_f32_16x16x32_bf16 v[108:111], v[186:189], v[198:201], v[108:111]
	v_mfma_f32_16x16x32_bf16 v[104:107], v[186:189], v[202:205], v[104:107]
	v_mfma_f32_16x16x32_bf16 v[84:87], v[186:189], v[206:209], v[84:87]
	v_mfma_f32_16x16x32_bf16 v[72:75], v[186:189], v[210:213], v[72:75]
	v_mfma_f32_16x16x32_bf16 v[60:63], v[186:189], v[214:217], v[60:63]
	v_mfma_f32_16x16x32_bf16 v[48:51], v[186:189], v[218:221], v[48:51]
	v_mfma_f32_16x16x32_bf16 v[36:39], v[186:189], v[222:225], v[36:39]
	v_mfma_f32_16x16x32_bf16 v[100:103], v[190:193], v[194:197], v[100:103]
	v_mfma_f32_16x16x32_bf16 v[96:99], v[190:193], v[198:201], v[96:99]
	v_mfma_f32_16x16x32_bf16 v[92:95], v[190:193], v[202:205], v[92:95]
	v_mfma_f32_16x16x32_bf16 v[88:91], v[190:193], v[206:209], v[88:91]
	v_mfma_f32_16x16x32_bf16 v[76:79], v[190:193], v[210:213], v[76:79]
	v_mfma_f32_16x16x32_bf16 v[64:67], v[190:193], v[214:217], v[64:67]
	v_mfma_f32_16x16x32_bf16 v[52:55], v[190:193], v[218:221], v[52:55]
	v_mfma_f32_16x16x32_bf16 v[40:43], v[190:193], v[222:225], v[40:43]
	s_add_u32 s14, s14, 64
	s_addc_u32 s15, s15, 0
	s_cmpk_eq_i32 s14, 0xfc0
	s_waitcnt vmcnt(0)
	s_barrier
	s_cbranch_scc0 .LBB0_713
	ds_read_b128 v[146:149], v143 offset:23552
	ds_read_b128 v[178:181], v143 offset:22528
	ds_read_b128 v[182:185], v143 offset:21504
	ds_read_b128 v[186:189], v143 offset:20480
	ds_read_b128 v[190:193], v143 offset:19456
	ds_read_b128 v[194:197], v143 offset:18432
	ds_read_b128 v[198:201], v143 offset:17408
	ds_read_b128 v[202:205], v143 offset:16384
	ds_read_b128 v[206:209], v136 offset:44032
	ds_read_b128 v[210:213], v136 offset:43008
	ds_read_b128 v[214:217], v136 offset:41984
	ds_read_b128 v[218:221], v136 offset:40960
	s_waitcnt lgkmcnt(0)
	v_mfma_f32_16x16x32_bf16 v[28:31], v[218:221], v[202:205], v[28:31]
	v_mfma_f32_16x16x32_bf16 v[24:27], v[218:221], v[198:201], v[24:27]
	v_mfma_f32_16x16x32_bf16 v[20:23], v[218:221], v[194:197], v[20:23]
	v_mfma_f32_16x16x32_bf16 v[16:19], v[218:221], v[190:193], v[16:19]
	v_mfma_f32_16x16x32_bf16 v[12:15], v[218:221], v[186:189], v[12:15]
	v_mfma_f32_16x16x32_bf16 v[8:11], v[218:221], v[182:185], v[8:11]
	v_mfma_f32_16x16x32_bf16 v[4:7], v[218:221], v[178:181], v[4:7]
	v_mfma_f32_16x16x32_bf16 v[0:3], v[218:221], v[146:149], v[0:3]
	v_mfma_f32_16x16x32_bf16 v[124:127], v[214:217], v[202:205], v[124:127]
	v_mfma_f32_16x16x32_bf16 v[120:123], v[214:217], v[198:201], v[120:123]
	v_mfma_f32_16x16x32_bf16 v[116:119], v[214:217], v[194:197], v[116:119]
	v_mfma_f32_16x16x32_bf16 v[80:83], v[214:217], v[190:193], v[80:83]
	v_mfma_f32_16x16x32_bf16 v[68:71], v[214:217], v[186:189], v[68:71]
	v_mfma_f32_16x16x32_bf16 v[56:59], v[214:217], v[182:185], v[56:59]
	v_mfma_f32_16x16x32_bf16 v[44:47], v[214:217], v[178:181], v[44:47]
	v_mfma_f32_16x16x32_bf16 v[32:35], v[214:217], v[146:149], v[32:35]
	v_mfma_f32_16x16x32_bf16 v[112:115], v[210:213], v[202:205], v[112:115]
	v_mfma_f32_16x16x32_bf16 v[108:111], v[210:213], v[198:201], v[108:111]
	v_mfma_f32_16x16x32_bf16 v[104:107], v[210:213], v[194:197], v[104:107]
	v_mfma_f32_16x16x32_bf16 v[84:87], v[210:213], v[190:193], v[84:87]
	v_mfma_f32_16x16x32_bf16 v[72:75], v[210:213], v[186:189], v[72:75]
	v_mfma_f32_16x16x32_bf16 v[60:63], v[210:213], v[182:185], v[60:63]
	v_mfma_f32_16x16x32_bf16 v[48:51], v[210:213], v[178:181], v[48:51]
	v_mfma_f32_16x16x32_bf16 v[36:39], v[210:213], v[146:149], v[36:39]
	v_mfma_f32_16x16x32_bf16 v[100:103], v[206:209], v[202:205], v[100:103]
	v_mfma_f32_16x16x32_bf16 v[96:99], v[206:209], v[198:201], v[96:99]
	v_mfma_f32_16x16x32_bf16 v[92:95], v[206:209], v[194:197], v[92:95]
	v_mfma_f32_16x16x32_bf16 v[88:91], v[206:209], v[190:193], v[88:91]
	v_mfma_f32_16x16x32_bf16 v[76:79], v[206:209], v[186:189], v[76:79]
	v_mfma_f32_16x16x32_bf16 v[64:67], v[206:209], v[182:185], v[64:67]
	v_mfma_f32_16x16x32_bf16 v[52:55], v[206:209], v[178:181], v[52:55]
	v_mfma_f32_16x16x32_bf16 v[40:43], v[206:209], v[146:149], v[40:43]
	s_lshl_b32 s1, s70, 8
	s_add_i32 s0, s0, s1
	s_and_b32 s6, s0, 0x1f80
	s_ashr_i32 s0, s0, 9
	s_lshr_b32 s7, s71, 3
	s_and_b32 s72, s0, -16
	s_cmp_lg_u32 s7, 6
	s_mov_b64 s[14:15], -1
	s_barrier
	s_cbranch_scc0 .LBB0_774
	s_cmp_lt_u32 s71, 8
	s_cselect_b64 s[14:15], -1, 0
	s_mov_b64 s[16:17], 0xc0
	s_and_b64 vcc, exec, s[14:15]
	s_cbranch_vccnz .LBB0_728
	s_cmp_lt_i32 s7, 3
	s_cbranch_scc1 .LBB0_721
	s_cmp_gt_i32 s7, 3
	s_cbranch_scc0 .LBB0_722
	s_cmp_eq_u32 s7, 4
	s_mov_b64 s[52:53], -1
	s_cbranch_scc0 .LBB0_720
	s_mov_b64 s[52:53], 0

.LBB0_907:
	s_and_b32 s17, s16, 1
	s_xor_b32 s18, s17, 1
	s_lshl_b32 s33, s18, 14
	v_lshl_add_u64 v[150:151], v[146:147], 0, s[14:15]
	s_add_i32 s33, s6, s33
	v_lshl_add_u64 v[178:179], v[150:151], 0, 64
	s_mov_b32 m0, s33
	v_lshl_add_u64 v[180:181], v[150:151], 0, s[38:39]
	global_load_lds_dwordx4 v[178:179], off
	s_add_i32 m0, s33, 0x400
	v_lshl_add_u64 v[182:183], v[150:151], 0, s[40:41]
	s_lshl_b32 s18, s18, 13
	global_load_lds_dwordx4 v[180:181], off
	s_add_i32 m0, s33, 0x800
	v_lshl_add_u64 v[172:173], v[148:149], 0, s[14:15]
	v_lshl_add_u64 v[150:151], v[150:151], 0, s[42:43]
	s_add_i32 s18, s7, s18
	global_load_lds_dwordx4 v[182:183], off
	s_add_i32 m0, s33, 0xc00
	v_lshl_add_u64 v[184:185], v[172:173], 0, 64
	global_load_lds_dwordx4 v[150:151], off
	s_add_i32 m0, s18, 0x8000
	v_lshl_add_u64 v[172:173], v[172:173], 0, s[38:39]
	global_load_lds_dwordx4 v[184:185], off
	s_add_i32 m0, s18, 0x8400
	v_lshl_add_u32 v145, s17, 14, v136
	global_load_lds_dwordx4 v[172:173], off
	v_lshl_or_b32 v150, s17, 13, v143
	ds_read_b128 v[178:181], v145
	ds_read_b128 v[182:185], v145 offset:1024
	ds_read_b128 v[186:189], v145 offset:2048
	ds_read_b128 v[190:193], v145 offset:3072
	ds_read_b128 v[194:197], v145 offset:4096
	ds_read_b128 v[198:201], v145 offset:5120
	ds_read_b128 v[202:205], v145 offset:6144
	ds_read_b128 v[206:209], v145 offset:7168
	ds_read_b128 v[210:213], v150 offset:32768
	ds_read_b128 v[214:217], v150 offset:33792
	ds_read_b128 v[218:221], v150 offset:34816
	ds_read_b128 v[222:225], v150 offset:35840
	s_add_i32 s16, s16, 1
	s_waitcnt lgkmcnt(0)
	v_mfma_f32_16x16x32_bf16 v[124:127], v[178:181], v[210:213], v[124:127]
	v_mfma_f32_16x16x32_bf16 v[120:123], v[178:181], v[214:217], v[120:123]
	v_mfma_f32_16x16x32_bf16 v[116:119], v[178:181], v[218:221], v[116:119]
	v_mfma_f32_16x16x32_bf16 v[112:115], v[178:181], v[222:225], v[112:115]
	v_mfma_f32_16x16x32_bf16 v[108:111], v[182:185], v[210:213], v[108:111]
	v_mfma_f32_16x16x32_bf16 v[104:107], v[182:185], v[214:217], v[104:107]
	v_mfma_f32_16x16x32_bf16 v[100:103], v[182:185], v[218:221], v[100:103]
	v_mfma_f32_16x16x32_bf16 v[96:99], v[182:185], v[222:225], v[96:99]
	v_mfma_f32_16x16x32_bf16 v[92:95], v[186:189], v[210:213], v[92:95]
	v_mfma_f32_16x16x32_bf16 v[88:91], v[186:189], v[214:217], v[88:91]
	v_mfma_f32_16x16x32_bf16 v[84:87], v[186:189], v[218:221], v[84:87]
	v_mfma_f32_16x16x32_bf16 v[80:83], v[186:189], v[222:225], v[80:83]
	v_mfma_f32_16x16x32_bf16 v[76:79], v[190:193], v[210:213], v[76:79]
	v_mfma_f32_16x16x32_bf16 v[72:75], v[190:193], v[214:217], v[72:75]
	v_mfma_f32_16x16x32_bf16 v[68:71], v[190:193], v[218:221], v[68:71]
	v_mfma_f32_16x16x32_bf16 v[64:67], v[190:193], v[222:225], v[64:67]
	v_mfma_f32_16x16x32_bf16 v[60:63], v[194:197], v[210:213], v[60:63]
	v_mfma_f32_16x16x32_bf16 v[56:59], v[194:197], v[214:217], v[56:59]
	v_mfma_f32_16x16x32_bf16 v[52:55], v[194:197], v[218:221], v[52:55]
	v_mfma_f32_16x16x32_bf16 v[48:51], v[194:197], v[222:225], v[48:51]
	v_mfma_f32_16x16x32_bf16 v[44:47], v[198:201], v[210:213], v[44:47]
	v_mfma_f32_16x16x32_bf16 v[40:43], v[198:201], v[214:217], v[40:43]
	v_mfma_f32_16x16x32_bf16 v[36:39], v[198:201], v[218:221], v[36:39]
	v_mfma_f32_16x16x32_bf16 v[32:35], v[198:201], v[222:225], v[32:35]
	v_mfma_f32_16x16x32_bf16 v[28:31], v[202:205], v[210:213], v[28:31]
	v_mfma_f32_16x16x32_bf16 v[24:27], v[202:205], v[214:217], v[24:27]
	v_mfma_f32_16x16x32_bf16 v[20:23], v[202:205], v[218:221], v[20:23]
	v_mfma_f32_16x16x32_bf16 v[16:19], v[202:205], v[222:225], v[16:19]
	v_mfma_f32_16x16x32_bf16 v[12:15], v[206:209], v[210:213], v[12:15]
	v_mfma_f32_16x16x32_bf16 v[8:11], v[206:209], v[214:217], v[8:11]
	v_mfma_f32_16x16x32_bf16 v[4:7], v[206:209], v[218:221], v[4:7]
	v_mfma_f32_16x16x32_bf16 v[0:3], v[206:209], v[222:225], v[0:3]
	s_add_u32 s14, s14, 64
	s_addc_u32 s15, s15, 0
	s_cmpk_lg_i32 s14, 0xfc0
	s_waitcnt vmcnt(0)
	s_barrier
	s_cbranch_scc1 .LBB0_907
	ds_read_b128 v[146:149], v143 offset:44032
	ds_read_b128 v[178:181], v143 offset:43008
	ds_read_b128 v[182:185], v143 offset:41984
	ds_read_b128 v[186:189], v143 offset:40960
	ds_read_b128 v[190:193], v136 offset:23552
	ds_read_b128 v[194:197], v136 offset:22528
	ds_read_b128 v[198:201], v136 offset:21504
	ds_read_b128 v[202:205], v136 offset:20480
	ds_read_b128 v[206:209], v136 offset:19456
	ds_read_b128 v[210:213], v136 offset:18432
	ds_read_b128 v[214:217], v136 offset:17408
	ds_read_b128 v[218:221], v136 offset:16384
	s_waitcnt lgkmcnt(0)
	v_mfma_f32_16x16x32_bf16 v[124:127], v[218:221], v[186:189], v[124:127]
	v_mfma_f32_16x16x32_bf16 v[120:123], v[218:221], v[182:185], v[120:123]
	v_mfma_f32_16x16x32_bf16 v[116:119], v[218:221], v[178:181], v[116:119]
	v_mfma_f32_16x16x32_bf16 v[112:115], v[218:221], v[146:149], v[112:115]
	v_mfma_f32_16x16x32_bf16 v[108:111], v[214:217], v[186:189], v[108:111]
	v_mfma_f32_16x16x32_bf16 v[104:107], v[214:217], v[182:185], v[104:107]
	v_mfma_f32_16x16x32_bf16 v[100:103], v[214:217], v[178:181], v[100:103]
	v_mfma_f32_16x16x32_bf16 v[96:99], v[214:217], v[146:149], v[96:99]
	v_mfma_f32_16x16x32_bf16 v[92:95], v[210:213], v[186:189], v[92:95]
	v_mfma_f32_16x16x32_bf16 v[88:91], v[210:213], v[182:185], v[88:91]
	v_mfma_f32_16x16x32_bf16 v[84:87], v[210:213], v[178:181], v[84:87]
	v_mfma_f32_16x16x32_bf16 v[80:83], v[210:213], v[146:149], v[80:83]
	v_mfma_f32_16x16x32_bf16 v[76:79], v[206:209], v[186:189], v[76:79]
	v_mfma_f32_16x16x32_bf16 v[72:75], v[206:209], v[182:185], v[72:75]
	v_mfma_f32_16x16x32_bf16 v[210:213], v[206:209], v[178:181], v[68:71]
	v_mfma_f32_16x16x32_bf16 v[206:209], v[206:209], v[146:149], v[64:67]
	v_mfma_f32_16x16x32_bf16 v[60:63], v[202:205], v[186:189], v[60:63]
	v_mfma_f32_16x16x32_bf16 v[56:59], v[202:205], v[182:185], v[56:59]
	v_mfma_f32_16x16x32_bf16 v[52:55], v[202:205], v[178:181], v[52:55]
	v_mfma_f32_16x16x32_bf16 v[48:51], v[202:205], v[146:149], v[48:51]
	v_mfma_f32_16x16x32_bf16 v[44:47], v[198:201], v[186:189], v[44:47]
	v_mfma_f32_16x16x32_bf16 v[40:43], v[198:201], v[182:185], v[40:43]
	v_mfma_f32_16x16x32_bf16 v[36:39], v[198:201], v[178:181], v[36:39]
	v_mfma_f32_16x16x32_bf16 v[32:35], v[198:201], v[146:149], v[32:35]
	v_mfma_f32_16x16x32_bf16 v[28:31], v[194:197], v[186:189], v[28:31]
	v_mfma_f32_16x16x32_bf16 v[24:27], v[194:197], v[182:185], v[24:27]
	v_mfma_f32_16x16x32_bf16 v[20:23], v[194:197], v[178:181], v[20:23]
	v_mfma_f32_16x16x32_bf16 v[16:19], v[194:197], v[146:149], v[16:19]
	v_mfma_f32_16x16x32_bf16 v[12:15], v[190:193], v[186:189], v[12:15]
	v_mfma_f32_16x16x32_bf16 v[8:11], v[190:193], v[182:185], v[8:11]
	v_mfma_f32_16x16x32_bf16 v[4:7], v[190:193], v[178:181], v[4:7]
	v_mfma_f32_16x16x32_bf16 v[0:3], v[190:193], v[146:149], v[0:3]
	v_and_b32_e32 v65, 64, v167
	v_xor_b32_e32 v64, 16, v167
	v_add_u32_e32 v65, 64, v65
	v_cmp_lt_i32_e32 vcc, v64, v65
	v_cvt_pk_bf16_f32 v65, v126, v127
	v_cvt_pk_bf16_f32 v67, v110, v111
	v_cndmask_b32_e32 v64, v167, v64, vcc
	s_lshl_b32 s7, s70, 8
	v_lshlrev_b32_e32 v136, 2, v64
	v_cvt_pk_bf16_f32 v64, v124, v125
	v_cvt_pk_bf16_f32 v66, v108, v109
	v_cndmask_b32_e64 v68, v65, v67, s[10:11]
	s_add_i32 s1, s1, s7
	v_cndmask_b32_e64 v69, v64, v66, s[10:11]
	ds_bpermute_b32 v70, v136, v68
	s_lshl_b32 s6, s71, 1
	s_and_b32 s7, s1, 0x1f80
	s_ashr_i32 s1, s1, 9
	ds_bpermute_b32 v71, v136, v69
	s_and_b32 s6, s6, 14
	s_and_b32 s1, s1, 0x3fffff0
	s_or_b32 s1, s6, s1
	s_or_b32 s0, s1, s0
	v_cndmask_b32_e64 v65, v67, v65, s[10:11]
	v_lshl_or_b32 v108, s0, 6, v129
	v_cndmask_b32_e64 v64, v66, v64, s[10:11]
	s_waitcnt lgkmcnt(1)
	v_cndmask_b32_e64 v69, v65, v70, s[10:11]
	v_cndmask_b32_e64 v67, v70, v65, s[10:11]
	v_cvt_pk_bf16_f32 v70, v120, v121
	v_cvt_pk_bf16_f32 v104, v104, v105
	s_waitcnt lgkmcnt(0)
	v_cndmask_b32_e64 v68, v64, v71, s[10:11]
	v_cndmask_b32_e64 v66, v71, v64, s[10:11]
	v_ashrrev_i32_e32 v109, 31, v108
	v_cvt_pk_bf16_f32 v71, v122, v123
	v_cvt_pk_bf16_f32 v105, v106, v107
	v_cndmask_b32_e64 v107, v70, v104, s[10:11]
	v_lshlrev_b64 v[64:65], 14, v[108:109]
	v_cndmask_b32_e64 v106, v71, v105, s[10:11]
	ds_bpermute_b32 v107, v136, v107
	v_lshl_add_u64 v[64:65], s[28:29], 0, v[64:65]
	s_lshl_b32 s18, s7, 1
	ds_bpermute_b32 v106, v136, v106
	v_lshl_add_u64 v[64:65], v[64:65], 0, s[18:19]
	v_mov_b32_e32 v143, v137
	v_lshl_add_u64 v[64:65], v[64:65], 0, v[142:143]
	s_waitcnt lgkmcnt(0)
	s_barrier
	global_store_dwordx4 v[64:65], v[66:69], off
	v_cvt_pk_bf16_f32 v92, v92, v93
	v_cvt_pk_bf16_f32 v93, v94, v95
	v_cndmask_b32_e64 v66, v104, v70, s[10:11]
	v_cndmask_b32_e64 v67, v105, v71, s[10:11]
	v_cndmask_b32_e64 v70, v66, v107, s[10:11]
	v_cndmask_b32_e64 v68, v107, v66, s[10:11]
	v_or_b32_e32 v66, 16, v108
	v_cndmask_b32_e64 v71, v67, v106, s[10:11]
	v_cndmask_b32_e64 v69, v106, v67, s[10:11]
	v_ashrrev_i32_e32 v67, 31, v66
	v_cvt_pk_bf16_f32 v76, v76, v77
	v_cvt_pk_bf16_f32 v77, v78, v79
	v_lshlrev_b64 v[66:67], 14, v[66:67]
	v_cndmask_b32_e64 v78, v93, v77, s[10:11]
	v_cndmask_b32_e64 v79, v92, v76, s[10:11]
	v_lshl_add_u64 v[66:67], s[28:29], 0, v[66:67]
	ds_bpermute_b32 v94, v136, v78
	ds_bpermute_b32 v95, v136, v79
	v_cvt_pk_bf16_f32 v88, v88, v89
	v_cvt_pk_bf16_f32 v89, v90, v91
	v_cvt_pk_bf16_f32 v72, v72, v73
	v_cvt_pk_bf16_f32 v73, v74, v75
	v_cvt_pk_bf16_f32 v60, v60, v61
	v_cvt_pk_bf16_f32 v61, v62, v63
	v_cvt_pk_bf16_f32 v44, v44, v45
	v_cvt_pk_bf16_f32 v45, v46, v47
	v_cvt_pk_bf16_f32 v56, v56, v57
	v_cvt_pk_bf16_f32 v57, v58, v59
	v_cvt_pk_bf16_f32 v40, v40, v41
	v_cvt_pk_bf16_f32 v41, v42, v43
	v_cvt_pk_bf16_f32 v28, v28, v29
	v_cvt_pk_bf16_f32 v29, v30, v31
	v_cvt_pk_bf16_f32 v12, v12, v13
	v_cvt_pk_bf16_f32 v13, v14, v15
	v_cvt_pk_bf16_f32 v24, v24, v25
	v_cvt_pk_bf16_f32 v25, v26, v27
	v_cvt_pk_bf16_f32 v8, v8, v9
	v_cvt_pk_bf16_f32 v9, v10, v11
	v_lshl_add_u64 v[66:67], v[66:67], 0, s[18:19]
	v_cvt_pk_bf16_f32 v104, v116, v117
	v_cvt_pk_bf16_f32 v100, v100, v101
	v_cndmask_b32_e64 v74, v89, v73, s[10:11]
	v_cndmask_b32_e64 v75, v88, v72, s[10:11]
	v_cndmask_b32_e64 v46, v61, v45, s[10:11]
	v_cndmask_b32_e64 v47, v60, v44, s[10:11]
	v_cndmask_b32_e64 v42, v57, v41, s[10:11]
	v_cndmask_b32_e64 v43, v56, v40, s[10:11]
	v_cndmask_b32_e64 v14, v29, v13, s[10:11]
	v_cndmask_b32_e64 v15, v28, v12, s[10:11]
	v_cndmask_b32_e64 v10, v25, v9, s[10:11]
	v_cndmask_b32_e64 v11, v24, v8, s[10:11]
	v_lshl_add_u64 v[66:67], v[66:67], 0, v[142:143]
	v_cvt_pk_bf16_f32 v105, v118, v119
	v_cvt_pk_bf16_f32 v101, v102, v103
	v_cndmask_b32_e64 v103, v104, v100, s[10:11]
	ds_bpermute_b32 v90, v136, v74
	ds_bpermute_b32 v91, v136, v75
	ds_bpermute_b32 v62, v136, v46
	ds_bpermute_b32 v63, v136, v47
	ds_bpermute_b32 v58, v136, v42
	ds_bpermute_b32 v59, v136, v43
	ds_bpermute_b32 v30, v136, v14
	ds_bpermute_b32 v31, v136, v15
	ds_bpermute_b32 v26, v136, v10
	ds_bpermute_b32 v27, v136, v11
	v_cndmask_b32_e64 v102, v105, v101, s[10:11]
	ds_bpermute_b32 v107, v136, v103
	global_store_dwordx4 v[66:67], v[68:71], off
	v_cvt_pk_bf16_f32 v96, v96, v97
	ds_bpermute_b32 v106, v136, v102
	v_cvt_pk_bf16_f32 v70, v112, v113
	v_cvt_pk_bf16_f32 v71, v114, v115
	v_cvt_pk_bf16_f32 v97, v98, v99
	v_cndmask_b32_e64 v99, v70, v96, s[10:11]
	v_cndmask_b32_e64 v76, v76, v92, s[10:11]
	v_cndmask_b32_e64 v77, v77, v93, s[10:11]
	v_cndmask_b32_e64 v69, v101, v105, s[10:11]
	v_cndmask_b32_e64 v98, v71, v97, s[10:11]
	ds_bpermute_b32 v105, v136, v99
	s_waitcnt lgkmcnt(14)
	v_cndmask_b32_e64 v79, v77, v94, s[10:11]
	s_waitcnt lgkmcnt(13)
	v_cndmask_b32_e64 v78, v76, v95, s[10:11]
	v_cndmask_b32_e64 v77, v94, v77, s[10:11]
	v_cndmask_b32_e64 v76, v95, v76, s[10:11]
	v_cndmask_b32_e64 v68, v100, v104, s[10:11]
	ds_bpermute_b32 v104, v136, v98
	global_store_dwordx4 v[64:65], v[76:79], off offset:64
	v_cndmask_b32_e64 v72, v72, v88, s[10:11]
	v_cndmask_b32_e64 v73, v73, v89, s[10:11]
	v_cvt_pk_bf16_f32 v76, v84, v85
	v_cvt_pk_bf16_f32 v77, v86, v87
	v_cvt_pk_bf16_f32 v78, v210, v211
	v_cvt_pk_bf16_f32 v79, v212, v213
	v_cndmask_b32_e64 v44, v44, v60, s[10:11]
	v_cndmask_b32_e64 v45, v45, v61, s[10:11]
	v_cndmask_b32_e64 v40, v40, v56, s[10:11]
	v_cndmask_b32_e64 v41, v41, v57, s[10:11]
	v_cndmask_b32_e64 v12, v12, v28, s[10:11]
	v_cndmask_b32_e64 v13, v13, v29, s[10:11]
	v_cndmask_b32_e64 v8, v8, v24, s[10:11]
	v_cndmask_b32_e64 v9, v9, v25, s[10:11]
	s_waitcnt lgkmcnt(13)
	v_cndmask_b32_e64 v75, v73, v90, s[10:11]
	s_waitcnt lgkmcnt(12)
	v_cndmask_b32_e64 v74, v72, v91, s[10:11]
	v_cndmask_b32_e64 v73, v90, v73, s[10:11]
	v_cndmask_b32_e64 v72, v91, v72, s[10:11]
	v_cndmask_b32_e64 v84, v77, v79, s[10:11]
	v_cndmask_b32_e64 v85, v76, v78, s[10:11]
	s_waitcnt lgkmcnt(11)
	v_cndmask_b32_e64 v47, v45, v62, s[10:11]
	s_waitcnt lgkmcnt(10)
	v_cndmask_b32_e64 v46, v44, v63, s[10:11]
	v_cndmask_b32_e64 v45, v62, v45, s[10:11]
	v_cndmask_b32_e64 v44, v63, v44, s[10:11]
	s_waitcnt lgkmcnt(9)
	v_cndmask_b32_e64 v43, v41, v58, s[10:11]
	s_waitcnt lgkmcnt(8)
	v_cndmask_b32_e64 v42, v40, v59, s[10:11]
	v_cndmask_b32_e64 v41, v58, v41, s[10:11]
	v_cndmask_b32_e64 v40, v59, v40, s[10:11]
	s_waitcnt lgkmcnt(7)
	v_cndmask_b32_e64 v15, v13, v30, s[10:11]
	s_waitcnt lgkmcnt(6)
	v_cndmask_b32_e64 v14, v12, v31, s[10:11]
	v_cndmask_b32_e64 v13, v30, v13, s[10:11]
	v_cndmask_b32_e64 v12, v31, v12, s[10:11]
	s_waitcnt lgkmcnt(5)
	v_cndmask_b32_e64 v11, v9, v26, s[10:11]
	s_waitcnt lgkmcnt(4)
	v_cndmask_b32_e64 v10, v8, v27, s[10:11]
	v_cndmask_b32_e64 v9, v26, v9, s[10:11]
	v_cndmask_b32_e64 v8, v27, v8, s[10:11]
	s_waitcnt lgkmcnt(3)
	v_cndmask_b32_e64 v102, v68, v107, s[10:11]
	v_cndmask_b32_e64 v100, v107, v68, s[10:11]
	v_or_b32_e32 v68, 32, v108
	ds_bpermute_b32 v84, v136, v84
	ds_bpermute_b32 v85, v136, v85
	global_store_dwordx4 v[66:67], v[72:75], off offset:64
	global_store_dwordx4 v[64:65], v[44:47], off offset:128
	v_cvt_pk_bf16_f32 v36, v36, v37
	v_cndmask_b32_e64 v72, v78, v76, s[10:11]
	v_cndmask_b32_e64 v73, v79, v77, s[10:11]
	v_cvt_pk_bf16_f32 v76, v80, v81
	v_cvt_pk_bf16_f32 v77, v82, v83
	v_cvt_pk_bf16_f32 v78, v206, v207
	v_cvt_pk_bf16_f32 v79, v208, v209
	v_cvt_pk_bf16_f32 v44, v52, v53
	v_cvt_pk_bf16_f32 v45, v54, v55
	v_cvt_pk_bf16_f32 v37, v38, v39
	global_store_dwordx4 v[66:67], v[40:43], off offset:128
	v_cvt_pk_bf16_f32 v32, v32, v33
	v_cvt_pk_bf16_f32 v33, v34, v35
	v_cvt_pk_bf16_f32 v40, v48, v49
	v_cvt_pk_bf16_f32 v41, v50, v51
	global_store_dwordx4 v[64:65], v[12:15], off offset:192
	v_cvt_pk_bf16_f32 v4, v4, v5
	v_cvt_pk_bf16_f32 v5, v6, v7
	v_cvt_pk_bf16_f32 v12, v20, v21
	v_cvt_pk_bf16_f32 v13, v22, v23
	global_store_dwordx4 v[66:67], v[8:11], off offset:192
	v_cvt_pk_bf16_f32 v0, v0, v1
	v_cvt_pk_bf16_f32 v1, v2, v3
	v_cvt_pk_bf16_f32 v8, v16, v17
	v_cvt_pk_bf16_f32 v9, v18, v19
	s_waitcnt lgkmcnt(4)
	v_cndmask_b32_e64 v103, v69, v106, s[10:11]
	v_cndmask_b32_e64 v101, v106, v69, s[10:11]
	v_ashrrev_i32_e32 v69, 31, v68
	v_cndmask_b32_e64 v70, v96, v70, s[10:11]
	v_cndmask_b32_e64 v80, v77, v79, s[10:11]
	v_cndmask_b32_e64 v81, v76, v78, s[10:11]
	v_cndmask_b32_e64 v38, v45, v37, s[10:11]
	v_cndmask_b32_e64 v39, v44, v36, s[10:11]
	v_cndmask_b32_e64 v34, v41, v33, s[10:11]
	v_cndmask_b32_e64 v35, v40, v32, s[10:11]
	v_cndmask_b32_e64 v6, v13, v5, s[10:11]
	v_cndmask_b32_e64 v7, v12, v4, s[10:11]
	v_cndmask_b32_e64 v2, v9, v1, s[10:11]
	v_cndmask_b32_e64 v3, v8, v0, s[10:11]
	v_lshlrev_b64 v[68:69], 14, v[68:69]
	v_cndmask_b32_e64 v71, v97, v71, s[10:11]
	s_waitcnt lgkmcnt(3)
	v_cndmask_b32_e64 v98, v70, v105, s[10:11]
	v_cndmask_b32_e64 v96, v105, v70, s[10:11]
	v_or_b32_e32 v70, 48, v108
	ds_bpermute_b32 v80, v136, v80
	ds_bpermute_b32 v81, v136, v81
	ds_bpermute_b32 v46, v136, v38
	ds_bpermute_b32 v47, v136, v39
	ds_bpermute_b32 v42, v136, v34
	ds_bpermute_b32 v43, v136, v35
	ds_bpermute_b32 v14, v136, v6
	ds_bpermute_b32 v15, v136, v7
	ds_bpermute_b32 v10, v136, v2
	ds_bpermute_b32 v11, v136, v3
	v_lshl_add_u64 v[68:69], s[28:29], 0, v[68:69]
	s_waitcnt lgkmcnt(12)
	v_cndmask_b32_e64 v99, v71, v104, s[10:11]
	v_cndmask_b32_e64 v97, v104, v71, s[10:11]
	v_ashrrev_i32_e32 v71, 31, v70
	v_lshl_add_u64 v[68:69], v[68:69], 0, s[18:19]
	v_lshlrev_b64 v[70:71], 14, v[70:71]
	v_lshl_add_u64 v[68:69], v[68:69], 0, v[142:143]
	v_lshl_add_u64 v[70:71], s[28:29], 0, v[70:71]
	s_waitcnt lgkmcnt(11)
	v_cndmask_b32_e64 v75, v73, v84, s[10:11]
	s_waitcnt lgkmcnt(10)
	v_cndmask_b32_e64 v74, v72, v85, s[10:11]
	v_cndmask_b32_e64 v73, v84, v73, s[10:11]
	v_cndmask_b32_e64 v72, v85, v72, s[10:11]
	v_lshl_add_u64 v[70:71], v[70:71], 0, s[18:19]
	global_store_dwordx4 v[68:69], v[72:75], off offset:64
	v_cndmask_b32_e64 v36, v36, v44, s[10:11]
	v_cndmask_b32_e64 v37, v37, v45, s[10:11]
	v_cndmask_b32_e64 v72, v78, v76, s[10:11]
	v_cndmask_b32_e64 v73, v79, v77, s[10:11]
	v_cndmask_b32_e64 v32, v32, v40, s[10:11]
	v_cndmask_b32_e64 v33, v33, v41, s[10:11]
	v_cndmask_b32_e64 v4, v4, v12, s[10:11]
	v_cndmask_b32_e64 v5, v5, v13, s[10:11]
	v_cndmask_b32_e64 v0, v0, v8, s[10:11]
	v_cndmask_b32_e64 v1, v1, v9, s[10:11]
	v_lshl_add_u64 v[70:71], v[70:71], 0, v[142:143]
	s_waitcnt lgkmcnt(9)
	v_cndmask_b32_e64 v75, v73, v80, s[10:11]
	s_waitcnt lgkmcnt(8)
	v_cndmask_b32_e64 v74, v72, v81, s[10:11]
	v_cndmask_b32_e64 v73, v80, v73, s[10:11]
	v_cndmask_b32_e64 v72, v81, v72, s[10:11]
	s_waitcnt lgkmcnt(7)
	v_cndmask_b32_e64 v39, v37, v46, s[10:11]
	s_waitcnt lgkmcnt(6)
	v_cndmask_b32_e64 v38, v36, v47, s[10:11]
	v_cndmask_b32_e64 v37, v46, v37, s[10:11]
	v_cndmask_b32_e64 v36, v47, v36, s[10:11]
	s_waitcnt lgkmcnt(5)
	v_cndmask_b32_e64 v35, v33, v42, s[10:11]
	s_waitcnt lgkmcnt(4)
	v_cndmask_b32_e64 v34, v32, v43, s[10:11]
	v_cndmask_b32_e64 v33, v42, v33, s[10:11]
	v_cndmask_b32_e64 v32, v43, v32, s[10:11]
	s_waitcnt lgkmcnt(3)
	v_cndmask_b32_e64 v7, v5, v14, s[10:11]
	s_waitcnt lgkmcnt(2)
	v_cndmask_b32_e64 v6, v4, v15, s[10:11]
	v_cndmask_b32_e64 v5, v14, v5, s[10:11]
	v_cndmask_b32_e64 v4, v15, v4, s[10:11]
	s_waitcnt lgkmcnt(1)
	v_cndmask_b32_e64 v3, v1, v10, s[10:11]
	s_waitcnt lgkmcnt(0)
	v_cndmask_b32_e64 v2, v0, v11, s[10:11]
	v_cndmask_b32_e64 v1, v10, v1, s[10:11]
	v_cndmask_b32_e64 v0, v11, v0, s[10:11]
	global_store_dwordx4 v[68:69], v[100:103], off
	global_store_dwordx4 v[70:71], v[96:99], off
	global_store_dwordx4 v[70:71], v[72:75], off offset:64
	global_store_dwordx4 v[68:69], v[36:39], off offset:128
	global_store_dwordx4 v[70:71], v[32:35], off offset:128
	global_store_dwordx4 v[68:69], v[4:7], off offset:192
	global_store_dwordx4 v[70:71], v[0:3], off offset:192
	s_branch .LBB0_705

.LBB0_1177:
	s_and_b32 s49, s48, 1
	s_xor_b32 s50, s49, 1
	s_lshl_b32 s51, s50, 14
	v_lshl_add_u64 v[150:151], v[136:137], 0, s[44:45]
	s_add_i32 s51, s33, s51
	v_lshl_add_u64 v[160:161], v[150:151], 0, 64
	s_mov_b32 m0, s51
	v_lshl_add_u64 v[162:163], v[150:151], 0, s[38:39]
	global_load_lds_dwordx4 v[160:161], off
	s_add_i32 m0, s51, 0x400
	v_lshl_add_u64 v[164:165], v[150:151], 0, s[40:41]
	s_lshl_b32 s50, s50, 13
	global_load_lds_dwordx4 v[162:163], off
	s_add_i32 m0, s51, 0x800
	v_lshl_add_u64 v[152:153], v[138:139], 0, s[44:45]
	v_lshl_add_u64 v[150:151], v[150:151], 0, s[42:43]
	s_add_i32 s50, s47, s50
	global_load_lds_dwordx4 v[164:165], off
	s_add_i32 m0, s51, 0xc00
	v_lshl_add_u64 v[166:167], v[152:153], 0, 64
	global_load_lds_dwordx4 v[150:151], off
	s_add_i32 m0, s50, 0x8000
	v_lshl_add_u64 v[152:153], v[152:153], 0, s[38:39]
	global_load_lds_dwordx4 v[166:167], off
	s_add_i32 m0, s50, 0x8400
	v_lshl_or_b32 v149, s49, 13, v147
	global_load_lds_dwordx4 v[152:153], off
	v_lshl_add_u32 v172, s49, 14, v148
	ds_read_b128 v[150:153], v149 offset:32768
	ds_read_b128 v[160:163], v149 offset:33792
	ds_read_b128 v[164:167], v149 offset:34816
	ds_read_b128 v[168:171], v149 offset:35840
	ds_read_b128 v[178:181], v172
	ds_read_b128 v[182:185], v172 offset:1024
	ds_read_b128 v[186:189], v172 offset:2048
	ds_read_b128 v[190:193], v172 offset:3072
	ds_read_b128 v[194:197], v172 offset:4096
	ds_read_b128 v[198:201], v172 offset:5120
	ds_read_b128 v[202:205], v172 offset:6144
	ds_read_b128 v[206:209], v172 offset:7168
	s_add_i32 s48, s48, 1
	s_waitcnt lgkmcnt(0)
	v_mfma_f32_16x16x32_bf16 v[124:127], v[150:153], v[178:181], v[124:127]
	v_mfma_f32_16x16x32_bf16 v[120:123], v[150:153], v[182:185], v[120:123]
	v_mfma_f32_16x16x32_bf16 v[116:119], v[150:153], v[186:189], v[116:119]
	v_mfma_f32_16x16x32_bf16 v[112:115], v[150:153], v[190:193], v[112:115]
	v_mfma_f32_16x16x32_bf16 v[60:63], v[150:153], v[194:197], v[60:63]
	v_mfma_f32_16x16x32_bf16 v[44:47], v[150:153], v[198:201], v[44:47]
	v_mfma_f32_16x16x32_bf16 v[28:31], v[150:153], v[202:205], v[28:31]
	v_mfma_f32_16x16x32_bf16 v[12:15], v[150:153], v[206:209], v[12:15]
	v_mfma_f32_16x16x32_bf16 v[108:111], v[160:163], v[178:181], v[108:111]
	v_mfma_f32_16x16x32_bf16 v[104:107], v[160:163], v[182:185], v[104:107]
	v_mfma_f32_16x16x32_bf16 v[100:103], v[160:163], v[186:189], v[100:103]
	v_mfma_f32_16x16x32_bf16 v[96:99], v[160:163], v[190:193], v[96:99]
	v_mfma_f32_16x16x32_bf16 v[56:59], v[160:163], v[194:197], v[56:59]
	v_mfma_f32_16x16x32_bf16 v[40:43], v[160:163], v[198:201], v[40:43]
	v_mfma_f32_16x16x32_bf16 v[24:27], v[160:163], v[202:205], v[24:27]
	v_mfma_f32_16x16x32_bf16 v[8:11], v[160:163], v[206:209], v[8:11]
	v_mfma_f32_16x16x32_bf16 v[92:95], v[164:167], v[178:181], v[92:95]
	v_mfma_f32_16x16x32_bf16 v[88:91], v[164:167], v[182:185], v[88:91]
	v_mfma_f32_16x16x32_bf16 v[84:87], v[164:167], v[186:189], v[84:87]
	v_mfma_f32_16x16x32_bf16 v[80:83], v[164:167], v[190:193], v[80:83]
	v_mfma_f32_16x16x32_bf16 v[52:55], v[164:167], v[194:197], v[52:55]
	v_mfma_f32_16x16x32_bf16 v[36:39], v[164:167], v[198:201], v[36:39]
	v_mfma_f32_16x16x32_bf16 v[20:23], v[164:167], v[202:205], v[20:23]
	v_mfma_f32_16x16x32_bf16 v[4:7], v[164:167], v[206:209], v[4:7]
	v_mfma_f32_16x16x32_bf16 v[76:79], v[168:171], v[178:181], v[76:79]
	v_mfma_f32_16x16x32_bf16 v[72:75], v[168:171], v[182:185], v[72:75]
	v_mfma_f32_16x16x32_bf16 v[68:71], v[168:171], v[186:189], v[68:71]
	v_mfma_f32_16x16x32_bf16 v[64:67], v[168:171], v[190:193], v[64:67]
	v_mfma_f32_16x16x32_bf16 v[48:51], v[168:171], v[194:197], v[48:51]
	v_mfma_f32_16x16x32_bf16 v[32:35], v[168:171], v[198:201], v[32:35]
	v_mfma_f32_16x16x32_bf16 v[16:19], v[168:171], v[202:205], v[16:19]
	v_mfma_f32_16x16x32_bf16 v[0:3], v[168:171], v[206:209], v[0:3]
	s_add_u32 s44, s44, 64
	s_addc_u32 s45, s45, 0
	s_cmpk_eq_i32 s44, 0xfc0
	s_waitcnt vmcnt(0)
	s_barrier
	s_cbranch_scc0 .LBB0_1177
	ds_read_b128 v[136:139], v148 offset:23552
	ds_read_b128 v[150:153], v148 offset:22528
	ds_read_b128 v[160:163], v148 offset:21504
	ds_read_b128 v[164:167], v148 offset:20480
	ds_read_b128 v[168:171], v148 offset:19456
	ds_read_b128 v[178:181], v148 offset:18432
	ds_read_b128 v[182:185], v148 offset:17408
	ds_read_b128 v[186:189], v148 offset:16384
	ds_read_b128 v[190:193], v147 offset:44032
	ds_read_b128 v[194:197], v147 offset:43008
	ds_read_b128 v[198:201], v147 offset:41984
	ds_read_b128 v[202:205], v147 offset:40960
	s_waitcnt lgkmcnt(0)
	v_mfma_f32_16x16x32_bf16 v[120:123], v[202:205], v[182:185], v[120:123]
	v_mfma_f32_16x16x32_bf16 v[116:119], v[202:205], v[178:181], v[116:119]
	v_mfma_f32_16x16x32_bf16 v[112:115], v[202:205], v[168:171], v[112:115]
	v_mfma_f32_16x16x32_bf16 v[60:63], v[202:205], v[164:167], v[60:63]
	v_mfma_f32_16x16x32_bf16 v[44:47], v[202:205], v[160:163], v[44:47]
	v_mfma_f32_16x16x32_bf16 v[28:31], v[202:205], v[150:153], v[28:31]
	v_mfma_f32_16x16x32_bf16 v[12:15], v[202:205], v[136:139], v[12:15]
	v_mfma_f32_16x16x32_bf16 v[104:107], v[198:201], v[182:185], v[104:107]
	v_mfma_f32_16x16x32_bf16 v[100:103], v[198:201], v[178:181], v[100:103]
	v_mfma_f32_16x16x32_bf16 v[96:99], v[198:201], v[168:171], v[96:99]
	v_mfma_f32_16x16x32_bf16 v[56:59], v[198:201], v[164:167], v[56:59]
	v_mfma_f32_16x16x32_bf16 v[40:43], v[198:201], v[160:163], v[40:43]
	v_mfma_f32_16x16x32_bf16 v[24:27], v[198:201], v[150:153], v[24:27]
	v_mfma_f32_16x16x32_bf16 v[8:11], v[198:201], v[136:139], v[8:11]
	v_mfma_f32_16x16x32_bf16 v[88:91], v[194:197], v[182:185], v[88:91]
	v_mfma_f32_16x16x32_bf16 v[84:87], v[194:197], v[178:181], v[84:87]
	v_mfma_f32_16x16x32_bf16 v[80:83], v[194:197], v[168:171], v[80:83]
	v_mfma_f32_16x16x32_bf16 v[52:55], v[194:197], v[164:167], v[52:55]
	v_mfma_f32_16x16x32_bf16 v[36:39], v[194:197], v[160:163], v[36:39]
	v_mfma_f32_16x16x32_bf16 v[20:23], v[194:197], v[150:153], v[20:23]
	v_mfma_f32_16x16x32_bf16 v[4:7], v[194:197], v[136:139], v[4:7]
	v_mfma_f32_16x16x32_bf16 v[72:75], v[190:193], v[182:185], v[72:75]
	v_mfma_f32_16x16x32_bf16 v[68:71], v[190:193], v[178:181], v[68:71]
	v_mfma_f32_16x16x32_bf16 v[64:67], v[190:193], v[168:171], v[64:67]
	v_mfma_f32_16x16x32_bf16 v[48:51], v[190:193], v[164:167], v[48:51]
	v_mfma_f32_16x16x32_bf16 v[32:35], v[190:193], v[160:163], v[32:35]
	v_mfma_f32_16x16x32_bf16 v[16:19], v[190:193], v[150:153], v[16:19]
	v_mfma_f32_16x16x32_bf16 v[0:3], v[190:193], v[136:139], v[0:3]
	v_mfma_f32_16x16x32_bf16 v[124:127], v[202:205], v[186:189], v[124:127]
	v_mfma_f32_16x16x32_bf16 v[108:111], v[198:201], v[186:189], v[108:111]
	v_mfma_f32_16x16x32_bf16 v[198:201], v[194:197], v[186:189], v[92:95]
	v_mfma_f32_16x16x32_bf16 v[186:189], v[190:193], v[186:189], v[76:79]
	s_lshl_b32 s0, s0, 8
	s_add_i32 s1, s1, s0
	s_lshl_b32 s33, s22, 7
	s_lshl_b32 s44, s46, 6
	v_or_b32_e32 v76, s1, v129
	s_or_b32 s33, s44, s33
	v_ashrrev_i32_e32 v77, 31, v76
	v_or_b32_e32 v92, s33, v159
	v_lshlrev_b64 v[78:79], 13, v[76:77]
	v_lshl_or_b32 v78, v92, 2, v78
	v_lshl_add_u64 v[94:95], s[10:11], 0, v[78:79]
	s_barrier
	global_load_dwordx4 v[136:139], v[94:95], off
	v_lshl_add_u64 v[78:79], s[12:13], 0, v[78:79]
	s_lshl_b32 s47, s22, 1
	s_lshl_b32 s22, s33, 1
	s_waitcnt vmcnt(0)
	v_pk_add_f32 v[126:127], v[126:127], v[138:139]
	v_pk_add_f32 v[124:125], v[124:125], v[136:137]
	global_store_dwordx4 v[78:79], v[124:127], off
	global_load_dwordx4 v[136:139], v[94:95], off offset:64
	v_cvt_pk_bf16_f32 v93, v124, v125
	v_mul_f32_e32 v125, v125, v125
	v_fmac_f32_e32 v125, v124, v124
	v_cvt_pk_bf16_f32 v147, v126, v127
	v_fmac_f32_e32 v125, v126, v126
	v_fmac_f32_e32 v125, v127, v127
	s_waitcnt vmcnt(0)
	v_pk_add_f32 v[110:111], v[110:111], v[138:139]
	v_pk_add_f32 v[108:109], v[108:109], v[136:137]
	global_store_dwordx4 v[78:79], v[108:111], off offset:64
	global_load_dwordx4 v[136:139], v[94:95], off offset:128
	v_cvt_pk_bf16_f32 v124, v108, v109
	v_cvt_pk_bf16_f32 v126, v110, v111
	v_mul_f32_e32 v109, v109, v109
	v_fmac_f32_e32 v109, v108, v108
	v_cndmask_b32_e32 v108, v147, v126, vcc
	v_cndmask_b32_e32 v127, v93, v124, vcc
	v_cndmask_b32_e32 v93, v124, v93, vcc
	ds_bpermute_b32 v108, v143, v108
	ds_bpermute_b32 v124, v143, v127
	v_fmac_f32_e32 v109, v110, v110
	v_cndmask_b32_e32 v126, v126, v147, vcc
	v_fmac_f32_e32 v109, v111, v111
	v_add_f32_e32 v147, v125, v109
	s_waitcnt lgkmcnt(1)
	v_cndmask_b32_e32 v111, v126, v108, vcc
	v_cndmask_b32_e32 v109, v108, v126, vcc
	s_waitcnt lgkmcnt(0)
	v_cndmask_b32_e32 v110, v93, v124, vcc
	v_cndmask_b32_e32 v108, v124, v93, vcc
	s_waitcnt vmcnt(0)
	v_pk_add_f32 v[138:139], v[200:201], v[138:139]
	v_pk_add_f32 v[136:137], v[198:199], v[136:137]
	global_store_dwordx4 v[78:79], v[136:139], off offset:128
	global_load_dwordx4 v[148:151], v[94:95], off offset:192
	v_lshlrev_b64 v[94:95], 12, v[76:77]
	v_cvt_pk_bf16_f32 v93, v136, v137
	v_mul_f32_e32 v137, v137, v137
	v_lshl_add_u64 v[94:95], s[16:17], 0, v[94:95]
	v_fmac_f32_e32 v137, v136, v136
	v_lshl_add_u64 v[94:95], v[94:95], 0, s[22:23]
	v_fmac_f32_e32 v137, v138, v138
	v_lshl_add_u64 v[94:95], v[94:95], 0, v[134:135]
	v_fmac_f32_e32 v137, v139, v139
	v_cvt_pk_bf16_f32 v152, v138, v139
	s_waitcnt vmcnt(0)
	v_pk_add_f32 v[126:127], v[188:189], v[150:151]
	v_pk_add_f32 v[124:125], v[186:187], v[148:149]
	global_store_dwordx4 v[78:79], v[124:127], off offset:192
	v_cvt_pk_bf16_f32 v78, v124, v125
	global_store_dwordx4 v[94:95], v[108:111], off
	v_mul_f32_e32 v125, v125, v125
	v_fmac_f32_e32 v125, v124, v124
	v_fmac_f32_e32 v125, v126, v126
	v_fmac_f32_e32 v125, v127, v127
	v_add_f32_e32 v110, v147, v137
	v_add_f32_e32 v110, v110, v125
	ds_bpermute_b32 v124, v143, v110
	v_cvt_pk_bf16_f32 v79, v126, v127
	v_cndmask_b32_e32 v108, v152, v79, vcc
	v_cndmask_b32_e32 v109, v93, v78, vcc
	ds_bpermute_b32 v108, v143, v108
	v_cndmask_b32_e32 v93, v78, v93, vcc
	ds_bpermute_b32 v126, v143, v109
	s_waitcnt lgkmcnt(2)
	v_add_f32_e32 v78, v110, v124
	v_cndmask_b32_e32 v125, v79, v152, vcc
	ds_bpermute_b32 v79, v144, v78
	s_waitcnt lgkmcnt(2)
	v_cndmask_b32_e32 v111, v125, v108, vcc
	v_cndmask_b32_e32 v109, v108, v125, vcc
	s_waitcnt lgkmcnt(1)
	v_cndmask_b32_e32 v110, v93, v126, vcc
	v_cndmask_b32_e32 v108, v126, v93, vcc
	global_store_dwordx4 v[94:95], v[108:111], off offset:64
	s_and_saveexec_b64 s[44:45], s[8:9]
	s_cbranch_execz .LBB0_1180
	s_waitcnt lgkmcnt(0)
	v_add_f32_e32 v93, v78, v79
	v_lshlrev_b64 v[78:79], 7, v[76:77]
	v_lshl_add_u64 v[78:79], s[18:19], 0, v[78:79]
	s_lshl_b32 s0, s47, 2
	s_mov_b32 s1, s23
	v_lshl_add_u64 v[78:79], v[78:79], 0, s[0:1]
	s_lshl_b32 s0, s46, 2
	v_lshl_add_u64 v[78:79], v[78:79], 0, s[0:1]
	global_store_dword v[78:79], v93, off

.LBB0_1249:
	s_and_b32 s39, s38, 1
	s_xor_b32 s40, s39, 1
	s_lshl_b32 s41, s40, 14
	v_lshl_add_u64 v[150:151], v[138:139], 0, s[34:35]
	s_add_i32 s41, s36, s41
	v_lshl_add_u64 v[156:157], v[150:151], 0, 64
	s_mov_b32 m0, s41
	v_lshl_add_u64 v[158:159], v[150:151], 0, s[26:27]
	global_load_lds_dwordx4 v[156:157], off
	s_add_i32 m0, s41, 0x400
	v_lshl_add_u64 v[160:161], v[150:151], 0, s[28:29]
	s_lshl_b32 s40, s40, 13
	global_load_lds_dwordx4 v[158:159], off
	s_add_i32 m0, s41, 0x800
	v_lshl_add_u64 v[152:153], v[140:141], 0, s[34:35]
	v_lshl_add_u64 v[150:151], v[150:151], 0, s[30:31]
	s_add_i32 s40, s37, s40
	global_load_lds_dwordx4 v[160:161], off
	s_add_i32 m0, s41, 0xc00
	v_lshl_add_u64 v[162:163], v[152:153], 0, 64
	global_load_lds_dwordx4 v[150:151], off
	s_add_i32 m0, s40, 0x8000
	v_lshl_add_u64 v[152:153], v[152:153], 0, s[26:27]
	global_load_lds_dwordx4 v[162:163], off
	s_add_i32 m0, s40, 0x8400
	v_lshl_or_b32 v134, s39, 13, v137
	global_load_lds_dwordx4 v[152:153], off
	v_lshl_add_u32 v149, s39, 14, v148
	ds_read_b128 v[150:153], v134 offset:32768
	ds_read_b128 v[156:159], v134 offset:33792
	ds_read_b128 v[160:163], v134 offset:34816
	ds_read_b128 v[164:167], v134 offset:35840
	ds_read_b128 v[168:171], v149
	ds_read_b128 v[178:181], v149 offset:1024
	ds_read_b128 v[182:185], v149 offset:2048
	ds_read_b128 v[186:189], v149 offset:3072
	ds_read_b128 v[190:193], v149 offset:4096
	ds_read_b128 v[194:197], v149 offset:5120
	ds_read_b128 v[198:201], v149 offset:6144
	ds_read_b128 v[202:205], v149 offset:7168
	s_add_i32 s38, s38, 1
	s_waitcnt lgkmcnt(0)
	v_mfma_f32_16x16x32_bf16 v[124:127], v[150:153], v[168:171], v[124:127]
	v_mfma_f32_16x16x32_bf16 v[120:123], v[150:153], v[178:181], v[120:123]
	v_mfma_f32_16x16x32_bf16 v[116:119], v[150:153], v[182:185], v[116:119]
	v_mfma_f32_16x16x32_bf16 v[112:115], v[150:153], v[186:189], v[112:115]
	v_mfma_f32_16x16x32_bf16 v[108:111], v[150:153], v[190:193], v[108:111]
	v_mfma_f32_16x16x32_bf16 v[104:107], v[150:153], v[194:197], v[104:107]
	v_mfma_f32_16x16x32_bf16 v[100:103], v[150:153], v[198:201], v[100:103]
	v_mfma_f32_16x16x32_bf16 v[96:99], v[150:153], v[202:205], v[96:99]
	v_mfma_f32_16x16x32_bf16 v[92:95], v[156:159], v[168:171], v[92:95]
	v_mfma_f32_16x16x32_bf16 v[88:91], v[156:159], v[178:181], v[88:91]
	v_mfma_f32_16x16x32_bf16 v[84:87], v[156:159], v[182:185], v[84:87]
	v_mfma_f32_16x16x32_bf16 v[80:83], v[156:159], v[186:189], v[80:83]
	v_mfma_f32_16x16x32_bf16 v[76:79], v[156:159], v[190:193], v[76:79]
	v_mfma_f32_16x16x32_bf16 v[72:75], v[156:159], v[194:197], v[72:75]
	v_mfma_f32_16x16x32_bf16 v[68:71], v[156:159], v[198:201], v[68:71]
	v_mfma_f32_16x16x32_bf16 v[64:67], v[156:159], v[202:205], v[64:67]
	v_mfma_f32_16x16x32_bf16 v[60:63], v[160:163], v[168:171], v[60:63]
	v_mfma_f32_16x16x32_bf16 v[56:59], v[160:163], v[178:181], v[56:59]
	v_mfma_f32_16x16x32_bf16 v[52:55], v[160:163], v[182:185], v[52:55]
	v_mfma_f32_16x16x32_bf16 v[48:51], v[160:163], v[186:189], v[48:51]
	v_mfma_f32_16x16x32_bf16 v[44:47], v[160:163], v[190:193], v[44:47]
	v_mfma_f32_16x16x32_bf16 v[40:43], v[160:163], v[194:197], v[40:43]
	v_mfma_f32_16x16x32_bf16 v[36:39], v[160:163], v[198:201], v[36:39]
	v_mfma_f32_16x16x32_bf16 v[32:35], v[160:163], v[202:205], v[32:35]
	v_mfma_f32_16x16x32_bf16 v[28:31], v[164:167], v[168:171], v[28:31]
	v_mfma_f32_16x16x32_bf16 v[24:27], v[164:167], v[178:181], v[24:27]
	v_mfma_f32_16x16x32_bf16 v[20:23], v[164:167], v[182:185], v[20:23]
	v_mfma_f32_16x16x32_bf16 v[16:19], v[164:167], v[186:189], v[16:19]
	v_mfma_f32_16x16x32_bf16 v[12:15], v[164:167], v[190:193], v[12:15]
	v_mfma_f32_16x16x32_bf16 v[8:11], v[164:167], v[194:197], v[8:11]
	v_mfma_f32_16x16x32_bf16 v[4:7], v[164:167], v[198:201], v[4:7]
	v_mfma_f32_16x16x32_bf16 v[0:3], v[164:167], v[202:205], v[0:3]
	s_add_u32 s34, s34, 64
	s_addc_u32 s35, s35, 0
	s_cmpk_lg_i32 s34, 0xfc0
	s_waitcnt vmcnt(0)
	s_barrier
	s_cbranch_scc1 .LBB0_1249
	ds_read_b128 v[138:141], v148 offset:23552
	ds_read_b128 v[150:153], v148 offset:22528
	ds_read_b128 v[156:159], v148 offset:21504
	ds_read_b128 v[160:163], v148 offset:20480
	ds_read_b128 v[164:167], v148 offset:19456
	ds_read_b128 v[168:171], v148 offset:18432
	ds_read_b128 v[178:181], v148 offset:17408
	ds_read_b128 v[182:185], v148 offset:16384
	ds_read_b128 v[186:189], v137 offset:44032
	ds_read_b128 v[190:193], v137 offset:43008
	ds_read_b128 v[194:197], v137 offset:41984
	ds_read_b128 v[198:201], v137 offset:40960
	s_waitcnt lgkmcnt(0)
	v_mfma_f32_16x16x32_bf16 v[124:127], v[198:201], v[182:185], v[124:127]
	v_mfma_f32_16x16x32_bf16 v[120:123], v[198:201], v[178:181], v[120:123]
	v_mfma_f32_16x16x32_bf16 v[116:119], v[198:201], v[168:171], v[116:119]
	v_mfma_f32_16x16x32_bf16 v[112:115], v[198:201], v[164:167], v[112:115]
	v_mfma_f32_16x16x32_bf16 v[108:111], v[198:201], v[160:163], v[108:111]
	v_mfma_f32_16x16x32_bf16 v[104:107], v[198:201], v[156:159], v[104:107]
	v_mfma_f32_16x16x32_bf16 v[100:103], v[198:201], v[150:153], v[100:103]
	v_mfma_f32_16x16x32_bf16 v[96:99], v[198:201], v[138:141], v[96:99]
	v_mfma_f32_16x16x32_bf16 v[92:95], v[194:197], v[182:185], v[92:95]
	v_mfma_f32_16x16x32_bf16 v[88:91], v[194:197], v[178:181], v[88:91]
	v_mfma_f32_16x16x32_bf16 v[84:87], v[194:197], v[168:171], v[84:87]
	v_mfma_f32_16x16x32_bf16 v[80:83], v[194:197], v[164:167], v[80:83]
	v_mfma_f32_16x16x32_bf16 v[76:79], v[194:197], v[160:163], v[76:79]
	v_mfma_f32_16x16x32_bf16 v[72:75], v[194:197], v[156:159], v[72:75]
	v_mfma_f32_16x16x32_bf16 v[68:71], v[194:197], v[150:153], v[68:71]
	v_mfma_f32_16x16x32_bf16 v[64:67], v[194:197], v[138:141], v[64:67]
	v_mfma_f32_16x16x32_bf16 v[60:63], v[190:193], v[182:185], v[60:63]
	v_mfma_f32_16x16x32_bf16 v[56:59], v[190:193], v[178:181], v[56:59]
	v_mfma_f32_16x16x32_bf16 v[52:55], v[190:193], v[168:171], v[52:55]
	v_mfma_f32_16x16x32_bf16 v[48:51], v[190:193], v[164:167], v[48:51]
	v_mfma_f32_16x16x32_bf16 v[44:47], v[190:193], v[160:163], v[44:47]
	v_mfma_f32_16x16x32_bf16 v[40:43], v[190:193], v[156:159], v[40:43]
	v_mfma_f32_16x16x32_bf16 v[36:39], v[190:193], v[150:153], v[36:39]
	v_mfma_f32_16x16x32_bf16 v[32:35], v[190:193], v[138:141], v[32:35]
	v_mfma_f32_16x16x32_bf16 v[28:31], v[186:189], v[182:185], v[28:31]
	v_mfma_f32_16x16x32_bf16 v[24:27], v[186:189], v[178:181], v[24:27]
	v_mfma_f32_16x16x32_bf16 v[20:23], v[186:189], v[168:171], v[20:23]
	v_mfma_f32_16x16x32_bf16 v[164:167], v[186:189], v[164:167], v[16:19]
	v_mfma_f32_16x16x32_bf16 v[12:15], v[186:189], v[160:163], v[12:15]
	v_mfma_f32_16x16x32_bf16 v[8:11], v[186:189], v[156:159], v[8:11]
	v_mfma_f32_16x16x32_bf16 v[4:7], v[186:189], v[150:153], v[4:7]
	v_mfma_f32_16x16x32_bf16 v[0:3], v[186:189], v[138:141], v[0:3]
	v_cvt_pk_bf16_f32 v124, v124, v125
	v_cvt_pk_bf16_f32 v125, v126, v127
	v_cvt_pk_bf16_f32 v92, v92, v93
	v_cvt_pk_bf16_f32 v93, v94, v95
	v_cndmask_b32_e32 v18, v125, v93, vcc
	v_cndmask_b32_e32 v19, v124, v92, vcc
	s_lshl_b32 s33, s33, 8
	ds_bpermute_b32 v126, v145, v18
	ds_bpermute_b32 v127, v145, v19
	s_add_i32 s16, s16, s33
	v_or_b32_e32 v16, s16, v129
	v_ashrrev_i32_e32 v17, 31, v16
	v_lshlrev_b64 v[18:19], 12, v[16:17]
	v_cndmask_b32_e32 v17, v92, v124, vcc
	v_cndmask_b32_e32 v92, v93, v125, vcc
	s_waitcnt lgkmcnt(1)
	v_cndmask_b32_e32 v95, v92, v126, vcc
	s_waitcnt lgkmcnt(0)
	v_cndmask_b32_e32 v94, v17, v127, vcc
	v_cndmask_b32_e32 v93, v126, v92, vcc
	v_cndmask_b32_e32 v92, v127, v17, vcc
	v_cvt_pk_bf16_f32 v17, v60, v61
	v_cvt_pk_bf16_f32 v60, v62, v63
	v_cvt_pk_bf16_f32 v28, v28, v29
	v_cvt_pk_bf16_f32 v29, v30, v31
	v_cndmask_b32_e32 v30, v60, v29, vcc
	v_cndmask_b32_e32 v31, v17, v28, vcc
	ds_bpermute_b32 v61, v145, v30
	ds_bpermute_b32 v62, v145, v31
	s_lshl_b32 s0, s0, 8
	s_lshl_b32 s1, s1, 7
	v_lshl_add_u64 v[18:19], s[12:13], 0, v[18:19]
	s_or_b32 s16, s1, s0
	v_lshl_add_u64 v[18:19], v[18:19], 0, s[16:17]
	v_mov_b32_e32 v137, v135
	v_cndmask_b32_e32 v17, v28, v17, vcc
	v_cndmask_b32_e32 v28, v29, v60, vcc
	v_lshl_add_u64 v[18:19], v[18:19], 0, v[136:137]
	s_waitcnt lgkmcnt(1)
	v_cndmask_b32_e32 v31, v28, v61, vcc
	s_waitcnt lgkmcnt(0)
	v_cndmask_b32_e32 v30, v17, v62, vcc
	v_cndmask_b32_e32 v29, v61, v28, vcc
	v_cndmask_b32_e32 v28, v62, v17, vcc
	s_barrier
	global_store_dwordx4 v[18:19], v[28:31], off offset:64
	v_cvt_pk_bf16_f32 v17, v120, v121
	v_cvt_pk_bf16_f32 v24, v24, v25
	v_cvt_pk_bf16_f32 v28, v122, v123
	v_cvt_pk_bf16_f32 v29, v88, v89
	v_cvt_pk_bf16_f32 v30, v90, v91
	v_cndmask_b32_e32 v31, v28, v30, vcc
	v_cndmask_b32_e32 v60, v17, v29, vcc
	ds_bpermute_b32 v61, v145, v31
	ds_bpermute_b32 v60, v145, v60
	v_cndmask_b32_e32 v17, v29, v17, vcc
	v_cndmask_b32_e32 v28, v30, v28, vcc
	v_cvt_pk_bf16_f32 v25, v26, v27
	s_waitcnt lgkmcnt(1)
	v_cndmask_b32_e32 v31, v28, v61, vcc
	s_waitcnt lgkmcnt(0)
	v_cndmask_b32_e32 v30, v17, v60, vcc
	v_cndmask_b32_e32 v29, v61, v28, vcc
	v_cndmask_b32_e32 v28, v60, v17, vcc
	v_cvt_pk_bf16_f32 v17, v56, v57
	v_cvt_pk_bf16_f32 v56, v58, v59
	v_cndmask_b32_e32 v26, v56, v25, vcc
	v_cndmask_b32_e32 v27, v17, v24, vcc
	global_store_dwordx4 v[18:19], v[92:95], off
	v_or_b32_e32 v18, 16, v16
	ds_bpermute_b32 v57, v145, v26
	ds_bpermute_b32 v58, v145, v27
	v_ashrrev_i32_e32 v19, 31, v18
	v_lshlrev_b64 v[18:19], 12, v[18:19]
	v_lshl_add_u64 v[18:19], s[12:13], 0, v[18:19]
	v_lshl_add_u64 v[18:19], v[18:19], 0, s[16:17]
	v_cndmask_b32_e32 v17, v24, v17, vcc
	v_cndmask_b32_e32 v24, v25, v56, vcc
	v_lshl_add_u64 v[18:19], v[18:19], 0, v[136:137]
	s_waitcnt lgkmcnt(1)
	v_cndmask_b32_e32 v27, v24, v57, vcc
	s_waitcnt lgkmcnt(0)
	v_cndmask_b32_e32 v26, v17, v58, vcc
	v_cndmask_b32_e32 v25, v57, v24, vcc
	v_cndmask_b32_e32 v24, v58, v17, vcc
	global_store_dwordx4 v[18:19], v[24:27], off offset:64
	v_cvt_pk_bf16_f32 v17, v116, v117
	global_store_dwordx4 v[18:19], v[28:31], off
	v_cvt_pk_bf16_f32 v24, v118, v119
	v_cvt_pk_bf16_f32 v25, v84, v85
	v_cvt_pk_bf16_f32 v26, v86, v87
	v_cndmask_b32_e32 v27, v24, v26, vcc
	v_cndmask_b32_e32 v28, v17, v25, vcc
	v_or_b32_e32 v18, 32, v16
	ds_bpermute_b32 v29, v145, v27
	ds_bpermute_b32 v28, v145, v28
	v_ashrrev_i32_e32 v19, 31, v18
	v_lshlrev_b64 v[18:19], 12, v[18:19]
	v_lshl_add_u64 v[18:19], s[12:13], 0, v[18:19]
	v_cndmask_b32_e32 v17, v25, v17, vcc
	v_cndmask_b32_e32 v24, v26, v24, vcc
	v_lshl_add_u64 v[18:19], v[18:19], 0, s[16:17]
	s_waitcnt lgkmcnt(1)
	v_cndmask_b32_e32 v27, v24, v29, vcc
	s_waitcnt lgkmcnt(0)
	v_cndmask_b32_e32 v26, v17, v28, vcc
	v_cndmask_b32_e32 v25, v29, v24, vcc
	v_cndmask_b32_e32 v24, v28, v17, vcc
	v_lshl_add_u64 v[28:29], v[18:19], 0, v[136:137]
	v_cvt_pk_bf16_f32 v17, v52, v53
	v_cvt_pk_bf16_f32 v18, v54, v55
	v_cvt_pk_bf16_f32 v19, v20, v21
	v_cvt_pk_bf16_f32 v20, v22, v23
	v_cndmask_b32_e32 v21, v18, v20, vcc
	v_cndmask_b32_e32 v22, v17, v19, vcc
	ds_bpermute_b32 v23, v145, v21
	ds_bpermute_b32 v22, v145, v22
	v_cndmask_b32_e32 v17, v19, v17, vcc
	v_cndmask_b32_e32 v18, v20, v18, vcc
	global_store_dwordx4 v[28:29], v[24:27], off
	s_waitcnt lgkmcnt(1)
	v_cndmask_b32_e32 v21, v18, v23, vcc
	s_waitcnt lgkmcnt(0)
	v_cndmask_b32_e32 v20, v17, v22, vcc
	v_cndmask_b32_e32 v19, v23, v18, vcc
	v_cndmask_b32_e32 v18, v22, v17, vcc
	global_store_dwordx4 v[28:29], v[18:21], off offset:64
	v_cvt_pk_bf16_f32 v17, v112, v113
	v_cvt_pk_bf16_f32 v24, v82, v83
	v_cvt_pk_bf16_f32 v20, v114, v115
	v_cvt_pk_bf16_f32 v21, v80, v81
	v_cndmask_b32_e32 v22, v20, v24, vcc
	v_cndmask_b32_e32 v23, v17, v21, vcc
	ds_bpermute_b32 v25, v145, v22
	ds_bpermute_b32 v26, v145, v23
	v_or_b32_e32 v18, 48, v16
	v_ashrrev_i32_e32 v19, 31, v18
	v_lshlrev_b64 v[22:23], 12, v[18:19]
	v_cndmask_b32_e32 v17, v21, v17, vcc
	v_cndmask_b32_e32 v18, v24, v20, vcc
	s_waitcnt lgkmcnt(1)
	v_cndmask_b32_e32 v21, v18, v25, vcc
	s_waitcnt lgkmcnt(0)
	v_cndmask_b32_e32 v20, v17, v26, vcc
	v_cndmask_b32_e32 v19, v25, v18, vcc
	v_cndmask_b32_e32 v18, v26, v17, vcc
	v_cvt_pk_bf16_f32 v17, v48, v49
	v_cvt_pk_bf16_f32 v24, v50, v51
	v_cvt_pk_bf16_f32 v25, v164, v165
	v_cvt_pk_bf16_f32 v26, v166, v167
	v_cndmask_b32_e32 v27, v24, v26, vcc
	v_cndmask_b32_e32 v28, v17, v25, vcc
	ds_bpermute_b32 v27, v145, v27
	ds_bpermute_b32 v28, v145, v28
	v_lshl_add_u64 v[22:23], s[12:13], 0, v[22:23]
	v_lshl_add_u64 v[22:23], v[22:23], 0, s[16:17]
	v_lshl_add_u64 v[22:23], v[22:23], 0, v[136:137]
	global_store_dwordx4 v[22:23], v[18:21], off
	v_cndmask_b32_e32 v17, v25, v17, vcc
	v_cvt_pk_bf16_f32 v12, v12, v13
	v_cndmask_b32_e32 v18, v26, v24, vcc
	s_waitcnt lgkmcnt(1)
	v_cndmask_b32_e32 v21, v18, v27, vcc
	s_waitcnt lgkmcnt(0)
	v_cndmask_b32_e32 v20, v17, v28, vcc
	v_cndmask_b32_e32 v19, v27, v18, vcc
	v_cndmask_b32_e32 v18, v28, v17, vcc
	global_store_dwordx4 v[22:23], v[18:21], off offset:64
	v_cvt_pk_bf16_f32 v17, v108, v109
	v_cvt_pk_bf16_f32 v24, v78, v79
	v_cvt_pk_bf16_f32 v20, v110, v111
	v_cvt_pk_bf16_f32 v21, v76, v77
	v_cndmask_b32_e32 v22, v20, v24, vcc
	v_cndmask_b32_e32 v23, v17, v21, vcc
	ds_bpermute_b32 v25, v145, v22
	ds_bpermute_b32 v26, v145, v23
	v_or_b32_e32 v18, 64, v16
	v_ashrrev_i32_e32 v19, 31, v18
	v_lshlrev_b64 v[22:23], 12, v[18:19]
	v_cndmask_b32_e32 v17, v21, v17, vcc
	v_cndmask_b32_e32 v18, v24, v20, vcc
	s_waitcnt lgkmcnt(1)
	v_cndmask_b32_e32 v21, v18, v25, vcc
	s_waitcnt lgkmcnt(0)
	v_cndmask_b32_e32 v20, v17, v26, vcc
	v_cndmask_b32_e32 v19, v25, v18, vcc
	v_cndmask_b32_e32 v18, v26, v17, vcc
	v_cvt_pk_bf16_f32 v17, v44, v45
	v_cvt_pk_bf16_f32 v24, v46, v47
	v_cvt_pk_bf16_f32 v13, v14, v15
	v_cndmask_b32_e32 v14, v24, v13, vcc
	v_cndmask_b32_e32 v15, v17, v12, vcc
	ds_bpermute_b32 v25, v145, v14
	ds_bpermute_b32 v26, v145, v15
	v_lshl_add_u64 v[22:23], s[12:13], 0, v[22:23]
	v_lshl_add_u64 v[22:23], v[22:23], 0, s[16:17]
	v_cndmask_b32_e32 v12, v12, v17, vcc
	v_cndmask_b32_e32 v13, v13, v24, vcc
	v_lshl_add_u64 v[22:23], v[22:23], 0, v[136:137]
	s_waitcnt lgkmcnt(1)
	v_cndmask_b32_e32 v15, v13, v25, vcc
	s_waitcnt lgkmcnt(0)
	v_cndmask_b32_e32 v14, v12, v26, vcc
	v_cndmask_b32_e32 v13, v25, v13, vcc
	v_cndmask_b32_e32 v12, v26, v12, vcc
	global_store_dwordx4 v[22:23], v[18:21], off
	global_store_dwordx4 v[22:23], v[12:15], off offset:64
	v_cvt_pk_bf16_f32 v17, v72, v73
	v_cvt_pk_bf16_f32 v20, v74, v75
	v_cvt_pk_bf16_f32 v14, v104, v105
	v_cvt_pk_bf16_f32 v15, v106, v107
	v_cndmask_b32_e32 v18, v15, v20, vcc
	v_cndmask_b32_e32 v19, v14, v17, vcc
	ds_bpermute_b32 v21, v145, v18
	ds_bpermute_b32 v22, v145, v19
	v_or_b32_e32 v12, 0x50, v16
	v_ashrrev_i32_e32 v13, 31, v12
	v_lshlrev_b64 v[18:19], 12, v[12:13]
	v_cndmask_b32_e32 v12, v17, v14, vcc
	v_cndmask_b32_e32 v13, v20, v15, vcc
	v_cvt_pk_bf16_f32 v17, v40, v41
	v_cvt_pk_bf16_f32 v20, v42, v43
	v_cvt_pk_bf16_f32 v8, v8, v9
	v_cvt_pk_bf16_f32 v9, v10, v11
	v_cndmask_b32_e32 v10, v20, v9, vcc
	v_cndmask_b32_e32 v11, v17, v8, vcc
	s_waitcnt lgkmcnt(1)
	v_cndmask_b32_e32 v15, v13, v21, vcc
	s_waitcnt lgkmcnt(0)
	v_cndmask_b32_e32 v14, v12, v22, vcc
	v_cndmask_b32_e32 v13, v21, v13, vcc
	v_cndmask_b32_e32 v12, v22, v12, vcc
	ds_bpermute_b32 v21, v145, v10
	ds_bpermute_b32 v22, v145, v11
	v_lshl_add_u64 v[18:19], s[12:13], 0, v[18:19]
	v_lshl_add_u64 v[18:19], v[18:19], 0, s[16:17]
	v_cndmask_b32_e32 v8, v8, v17, vcc
	v_cndmask_b32_e32 v9, v9, v20, vcc
	v_lshl_add_u64 v[18:19], v[18:19], 0, v[136:137]
	s_waitcnt lgkmcnt(1)
	v_cndmask_b32_e32 v11, v9, v21, vcc
	s_waitcnt lgkmcnt(0)
	v_cndmask_b32_e32 v10, v8, v22, vcc
	v_cndmask_b32_e32 v9, v21, v9, vcc
	v_cndmask_b32_e32 v8, v22, v8, vcc
	global_store_dwordx4 v[18:19], v[12:15], off
	global_store_dwordx4 v[18:19], v[8:11], off offset:64
	v_cvt_pk_bf16_f32 v4, v4, v5
	v_cvt_pk_bf16_f32 v14, v68, v69
	v_cvt_pk_bf16_f32 v10, v100, v101
	v_cvt_pk_bf16_f32 v11, v102, v103
	v_cvt_pk_bf16_f32 v15, v70, v71
	v_cndmask_b32_e32 v12, v11, v15, vcc
	v_cndmask_b32_e32 v13, v10, v14, vcc
	ds_bpermute_b32 v17, v145, v12
	ds_bpermute_b32 v18, v145, v13
	v_or_b32_e32 v8, 0x60, v16
	v_ashrrev_i32_e32 v9, 31, v8
	v_lshlrev_b64 v[12:13], 12, v[8:9]
	v_cndmask_b32_e32 v8, v14, v10, vcc
	v_cndmask_b32_e32 v9, v15, v11, vcc
	v_cvt_pk_bf16_f32 v14, v36, v37
	v_cvt_pk_bf16_f32 v15, v38, v39
	v_cvt_pk_bf16_f32 v5, v6, v7
	v_cndmask_b32_e32 v6, v15, v5, vcc
	v_cndmask_b32_e32 v7, v14, v4, vcc
	s_waitcnt lgkmcnt(1)
	v_cndmask_b32_e32 v11, v9, v17, vcc
	s_waitcnt lgkmcnt(0)
	v_cndmask_b32_e32 v10, v8, v18, vcc
	v_cndmask_b32_e32 v9, v17, v9, vcc
	v_cndmask_b32_e32 v8, v18, v8, vcc
	ds_bpermute_b32 v17, v145, v6
	ds_bpermute_b32 v18, v145, v7
	v_lshl_add_u64 v[12:13], s[12:13], 0, v[12:13]
	v_lshl_add_u64 v[12:13], v[12:13], 0, s[16:17]
	v_cndmask_b32_e32 v4, v4, v14, vcc
	v_cndmask_b32_e32 v5, v5, v15, vcc
	v_lshl_add_u64 v[12:13], v[12:13], 0, v[136:137]
	s_waitcnt lgkmcnt(1)
	v_cndmask_b32_e32 v7, v5, v17, vcc
	s_waitcnt lgkmcnt(0)
	v_cndmask_b32_e32 v6, v4, v18, vcc
	v_cndmask_b32_e32 v5, v17, v5, vcc
	v_cndmask_b32_e32 v4, v18, v4, vcc
	global_store_dwordx4 v[12:13], v[8:11], off
	global_store_dwordx4 v[12:13], v[4:7], off offset:64
	v_cvt_pk_bf16_f32 v0, v0, v1
	v_cvt_pk_bf16_f32 v10, v64, v65
	v_cvt_pk_bf16_f32 v6, v96, v97
	v_cvt_pk_bf16_f32 v7, v98, v99
	v_cvt_pk_bf16_f32 v11, v66, v67
	v_cndmask_b32_e32 v8, v7, v11, vcc
	v_cndmask_b32_e32 v9, v6, v10, vcc
	ds_bpermute_b32 v12, v145, v8
	ds_bpermute_b32 v13, v145, v9
	v_or_b32_e32 v4, 0x70, v16
	v_ashrrev_i32_e32 v5, 31, v4
	v_lshlrev_b64 v[8:9], 12, v[4:5]
	v_cndmask_b32_e32 v4, v10, v6, vcc
	v_cndmask_b32_e32 v5, v11, v7, vcc
	v_cvt_pk_bf16_f32 v10, v32, v33
	v_cvt_pk_bf16_f32 v11, v34, v35
	v_cvt_pk_bf16_f32 v1, v2, v3
	v_cndmask_b32_e32 v2, v11, v1, vcc
	v_cndmask_b32_e32 v3, v10, v0, vcc
	s_waitcnt lgkmcnt(1)
	v_cndmask_b32_e32 v7, v5, v12, vcc
	s_waitcnt lgkmcnt(0)
	v_cndmask_b32_e32 v6, v4, v13, vcc
	v_cndmask_b32_e32 v5, v12, v5, vcc
	v_cndmask_b32_e32 v4, v13, v4, vcc
	ds_bpermute_b32 v12, v145, v2
	ds_bpermute_b32 v13, v145, v3
	v_lshl_add_u64 v[8:9], s[12:13], 0, v[8:9]
	v_lshl_add_u64 v[8:9], v[8:9], 0, s[16:17]
	v_cndmask_b32_e32 v0, v0, v10, vcc
	v_cndmask_b32_e32 v1, v1, v11, vcc
	s_add_i32 s7, s7, s89
	s_xor_b64 s[8:9], s[8:9], s[18:19]
	v_lshl_add_u64 v[8:9], v[8:9], 0, v[136:137]
	s_waitcnt lgkmcnt(1)
	v_cndmask_b32_e32 v3, v1, v12, vcc
	s_waitcnt lgkmcnt(0)
	v_cndmask_b32_e32 v2, v0, v13, vcc
	v_cndmask_b32_e32 v1, v12, v1, vcc
	v_cndmask_b32_e32 v0, v13, v0, vcc
	s_cmpk_gt_u32 s7, 0xff
	global_store_dwordx4 v[8:9], v[4:7], off
	global_store_dwordx4 v[8:9], v[0:3], off offset:64
	s_cbranch_scc0 .LBB0_1248
